# v126 with the P10 norm-weight loads issued at the start of the unit's final MFMA block instead of at the tail
# speedup vs baseline: 1.0079x; 1.0079x over previous
.LBB0_991:
	s_or_b64 exec, exec, s[0:1]
	s_mov_b32 s61, s69
	v_lshl_add_u64 v[188:189], v[114:115], 0, s[60:61]
	global_load_dwordx4 v[198:201], v[188:189], off
	global_load_dwordx4 v[202:205], v[188:189], off offset:64
	global_load_dwordx4 v[208:211], v[188:189], off offset:128
	global_load_dwordx4 v[212:215], v[188:189], off offset:192
	s_waitcnt vmcnt(23)
	v_mfma_f32_16x16x32_bf16 v[8:11], v[8:11], v[76:79], v[84:87]
	s_waitcnt vmcnt(22)
	v_mfma_f32_16x16x32_bf16 v[8:11], v[12:15], v[72:75], v[8:11]
	s_waitcnt vmcnt(21) lgkmcnt(1)
	v_mfma_f32_16x16x32_bf16 v[8:11], v[16:19], v[68:71], v[8:11]
	s_waitcnt vmcnt(20) lgkmcnt(0)
	v_mfma_f32_16x16x32_bf16 v[16:19], v[20:23], v[64:67], v[8:11]
	s_waitcnt vmcnt(19)
	v_mfma_f32_16x16x32_bf16 v[8:11], v[32:35], v[76:79], v[88:91]
	s_waitcnt vmcnt(18)
	v_mfma_f32_16x16x32_bf16 v[8:11], v[36:39], v[72:75], v[8:11]
	s_nop 3
	v_mul_f32_e32 v32, v17, v17
	v_fmac_f32_e32 v32, v16, v16
	v_fmac_f32_e32 v32, v18, v18
	s_waitcnt vmcnt(17)
	v_mfma_f32_16x16x32_bf16 v[8:11], v[40:43], v[68:71], v[8:11]
	v_fmac_f32_e32 v32, v19, v19
	s_waitcnt vmcnt(16)
	v_mfma_f32_16x16x32_bf16 v[12:15], v[44:47], v[64:67], v[8:11]
	s_waitcnt vmcnt(15)
	v_mfma_f32_16x16x32_bf16 v[8:11], v[48:51], v[76:79], v[92:95]
	s_waitcnt vmcnt(14)
	v_mfma_f32_16x16x32_bf16 v[8:11], v[52:55], v[72:75], v[8:11]
	s_nop 3
	v_fmac_f32_e32 v32, v12, v12
	v_fmac_f32_e32 v32, v13, v13
	v_fmac_f32_e32 v32, v14, v14
	s_waitcnt vmcnt(11)
	v_mfma_f32_16x16x32_bf16 v[20:23], v[28:31], v[76:79], v[80:83]
	v_fmac_f32_e32 v32, v15, v15
	v_mfma_f32_16x16x32_bf16 v[8:11], v[56:59], v[68:71], v[8:11]
	s_waitcnt vmcnt(10)
	v_mfma_f32_16x16x32_bf16 v[20:23], v[24:27], v[72:75], v[20:23]
	v_mfma_f32_16x16x32_bf16 v[8:11], v[60:63], v[64:67], v[8:11]
	s_waitcnt vmcnt(9)
	v_mfma_f32_16x16x32_bf16 v[4:7], v[4:7], v[68:71], v[20:23]
	s_waitcnt vmcnt(8)
	v_mfma_f32_16x16x32_bf16 v[0:3], v[0:3], v[64:67], v[4:7]
	s_nop 3
	v_fmac_f32_e32 v32, v8, v8
	v_fmac_f32_e32 v32, v9, v9
	v_fmac_f32_e32 v32, v10, v10
	v_fmac_f32_e32 v32, v11, v11
	v_fmac_f32_e32 v32, v0, v0
	v_fmac_f32_e32 v32, v1, v1
	v_fmac_f32_e32 v32, v2, v2
	v_fmac_f32_e32 v32, v3, v3
	v_mov_b32_e32 v4, v32
	v_mov_b32_e32 v249, v32
	s_nop 1
	v_permlane16_swap_b32_e32 v4, v249
	s_waitcnt lgkmcnt(0)
	v_add_f32_e32 v4, v4, v249
	v_mov_b32_e32 v5, v4
	v_mov_b32_e32 v249, v4
	s_nop 1
	v_permlane32_swap_b32_e32 v5, v249
	s_and_saveexec_b64 s[0:1], s[12:13]
	s_cbranch_execz .LBB0_978
	s_waitcnt lgkmcnt(0)
	v_add_f32_e32 v4, v5, v249
	ds_write_b32 v141, v4 offset:57344
	s_branch .LBB0_978
